# SWA: wait for Q fragment loads before the key-tile loop instead of vmcnt(1)/(0) between QK MFMAs in every iteration
# speedup vs baseline: 1.0171x; 1.0000x over previous
; DI void phase_attn_swa(const Params& P, const float* sinks, bf16_t* og, unsigned char* smem, int L, int G) {
;     ...
;     int qt, bg; gqa_item(it, L, G, gi, qt, bg);
;     const int b = bg >> 2, g = bg & 3;
;     const int t0 = qt * 32, t = t0 + r, head = g * 4 + w;
;     const size_t tok = (size_t)b * SEQ + t;
;     bf16x8 qf[4];
; #pragma unroll
;     for (int ks = 0; ks < 4; ++ks) qf[ks] = *(const bf16x8*)(big + SW_Q + tok * 1024 + head * 64 + ks * 16 + 8 * h);
;     f32x16 o0, o1, s[2]; o_zero(o0, o1);
;     float m = sinks[head] * LOG2E, l = 1.f;
;     const bf16_t* kb = big + SW_K + (size_t)b * SEQ * 256 + g * 64;
;     const bf16_t* vb = big + SW_VT + (size_t)((b * 4 + g) * 64) * SEQ;
;     const int jlo = (t0 - 127 > 0 ? t0 - 127 : 0) >> 6, jhi = (t0 + 31) >> 6;
;     KVR R; kv64_fetch(R, kb, 256, vb, SEQ, jlo * 64, true, tid);
;     __syncthreads();
;     kv64_store(R, sK, sVt, tid);
;     if (jlo < jhi) kv64_fetch(R, kb, 256, vb, SEQ, jlo * 64 + 64, true, tid);
.LBB0_342:
	v_ashrrev_i32_e32 v0, 2, v2
	s_lshl_b32 s40, s41, 5
	v_ashrrev_i32_e32 v1, 31, v0
	v_or_b32_e32 v150, s40, v135
	v_lshlrev_b64 v[148:149], 11, v[0:1]
	v_mov_b32_e32 v151, v129
	v_and_b32_e32 v3, 3, v2
	v_lshl_add_u64 v[4:5], v[148:149], 0, v[150:151]
	v_lshl_or_b32 v173, v3, 2, v133
	v_lshlrev_b64 v[4:5], 11, v[4:5]
	s_max_i32 s0, s40, 0x7f
	v_lshl_add_u64 v[4:5], s[76:77], 0, v[4:5]
	v_lshlrev_b32_e32 v128, 7, v173
	v_lshlrev_b64 v[0:1], 20, v[0:1]
	v_lshlrev_b32_e32 v2, 6, v2
	s_add_i32 s46, s0, 0xffffff81
	v_lshl_add_u64 v[4:5], v[4:5], 0, v[128:129]
	v_lshl_add_u64 v[0:1], s[30:31], 0, v[0:1]
	v_lshlrev_b32_e32 v128, 7, v3
	v_ashrrev_i32_e32 v3, 31, v2
	s_and_b32 s38, s46, 0xffffffc0
	v_lshl_add_u64 v[12:13], v[4:5], 0, v[140:141]
	v_lshlrev_b32_e32 v4, 2, v173
	v_lshl_add_u64 v[0:1], v[0:1], 0, v[128:129]
	v_lshlrev_b64 v[2:3], 12, v[2:3]
	v_or_b32_e32 v128, s38, v158
	global_load_dwordx4 v[64:67], v[12:13], off
	global_load_dwordx4 v[68:71], v[12:13], off offset:32
	global_load_dword v10, v4, s[14:15]
	v_lshl_add_u64 v[4:5], s[34:35], 0, v[2:3]
	v_lshlrev_b64 v[2:3], 9, v[128:129]
	v_or_b32_e32 v128, s38, v159
	v_lshl_add_u64 v[2:3], v[0:1], 0, v[2:3]
	v_lshlrev_b64 v[6:7], 9, v[128:129]
	v_lshl_add_u64 v[2:3], v[2:3], 0, v[142:143]
	v_lshl_add_u64 v[6:7], v[0:1], 0, v[6:7]
	v_lshl_add_u64 v[6:7], v[6:7], 0, v[142:143]
	global_load_dwordx4 v[80:83], v[2:3], off
	global_load_dwordx4 v[84:87], v[6:7], off
	v_lshl_add_u64 v[2:3], v[4:5], 0, v[144:145]
	s_lshl_b64 s[0:1], s[38:39], 1
	v_lshl_add_u64 v[6:7], v[2:3], 0, s[0:1]
	v_lshl_add_u64 v[6:7], v[6:7], 0, v[142:143]
	v_lshl_add_u64 v[4:5], v[4:5], 0, v[146:147]
	global_load_dwordx4 v[88:91], v[6:7], off
	v_lshl_add_u64 v[8:9], v[4:5], 0, s[0:1]
	v_lshl_add_u64 v[8:9], v[8:9], 0, v[142:143]
	global_load_dwordx4 v[92:95], v[8:9], off
	global_load_dwordx4 v[72:75], v[12:13], off offset:64
	global_load_dwordx4 v[76:79], v[12:13], off offset:96
	s_lshr_b32 s41, s41, 1
	s_lshr_b32 s46, s46, 6
	s_cmp_ge_u32 s46, s41
	s_barrier
	s_waitcnt vmcnt(3)
	ds_write_b128 v160, v[88:91] offset:9216
	ds_write_b128 v160, v[80:83]
	ds_write_b128 v160, v[84:87] offset:4608
	s_waitcnt vmcnt(2)
	ds_write_b128 v160, v[92:95] offset:13824
	s_waitcnt vmcnt(0)
	s_cbranch_scc1 .LBB0_344
	s_add_i32 s0, s38, 64
	v_or_b32_e32 v128, s0, v158
	v_lshlrev_b64 v[12:13], 9, v[128:129]
	v_or_b32_e32 v128, s0, v159
	v_lshl_add_u64 v[12:13], v[0:1], 0, v[12:13]
	v_lshlrev_b64 v[14:15], 9, v[128:129]
	v_lshl_add_u64 v[12:13], v[12:13], 0, v[142:143]
	v_lshl_add_u64 v[14:15], v[0:1], 0, v[14:15]
	v_lshl_add_u64 v[14:15], v[14:15], 0, v[142:143]
	global_load_dwordx4 v[80:83], v[12:13], off
	global_load_dwordx4 v[84:87], v[14:15], off
	global_load_dwordx4 v[88:91], v[6:7], off offset:128
	global_load_dwordx4 v[92:95], v[8:9], off offset:128

; #define MFMA(a, b, c) __builtin_amdgcn_mfma_f32_32x32x16_bf16((a), (b), (c), 0, 0, 0)
; template <int DQK, bool MASKED, int MODE, class MF>
; DI void attn_step(const bf16_t* sK, const bf16_t* sVt, const bf16x8 (&qf)[DQK / 16], f32x16& o0, f32x16& o1, float& m, float& l,
;                   float sc, const MF& mf, int lane, f32x16 (&s)[2], float invl, bool lanevalid = true) {
;     ...
;   bf16x8 kf[2][DQK / 16];
; #pragma unroll
;   for (int sub = 0; sub < 2; ++sub)
; #pragma unroll
;     for (int ks = 0; ks < DQK / 16; ++ks) kf[sub][ks] = *(const bf16x8*)(sK + (sub * 32 + pr) * KST + ks * 16 + 8 * h);
;   __builtin_amdgcn_sched_barrier(0);
; #pragma unroll
;   for (int q = 0; q < 16; ++q) { s[0][q] = 0.f; s[1][q] = 0.f; }
; #pragma unroll
;   for (int ks = 0; ks < DQK / 16; ++ks) {
;     s[0] = MFMA(kf[0][ks], qf[ks], s[0]);
;     s[1] = MFMA(kf[1][ks], qf[ks], s[1]);
;   }
;   bf16x8 vf[2][2][2];
;   if (MODE != 1) {
; #pragma unroll
;     for (int sub = 0; sub < 2; ++sub)
; #pragma unroll
;       for (int s2 = 0; s2 < 2; ++s2) {
;         vf[sub][s2][0] = *(const bf16x8*)(sVt + r * 72 + sub * 32 + s2 * 16 + 8 * h);
;         vf[sub][s2][1] = *(const bf16x8*)(sVt + (32 + r) * 72 + sub * 32 + s2 * 16 + 8 * h);
;       }
;     __builtin_amdgcn_sched_barrier(0);
;   }
;   float mxr = -3.0e38f;
; #pragma unroll
;   for (int sub = 0; sub < 2; ++sub)
; #pragma unroll
;     for (int q = 0; q < 16; ++q) {
;       if (MASKED) { const int kk = sub * 32 + 16 * (q >> 3) + 8 * h + (q & 7); s[sub][q] = mf(kk) ? s[sub][q] : -3.0e38f; }
;       if (MODE != 2) mxr = fmaxf(mxr, s[sub][q]);
.LBB0_350:
	s_mulk_i32 s0, 0x4800
	v_add_u32_e32 v40, s0, v163
	ds_read_b128 v[32:35], v40
	ds_read_b128 v[96:99], v40 offset:32
	ds_read_b128 v[100:103], v40 offset:64
	ds_read_b128 v[104:107], v40 offset:96
	ds_read_b128 v[36:39], v40 offset:4608
	ds_read_b128 v[108:111], v40 offset:4640
	ds_read_b128 v[112:115], v40 offset:4672
	ds_read_b128 v[178:181], v40 offset:4704
	v_add_u32_e32 v116, s0, v137
	s_waitcnt lgkmcnt(7)
	v_mfma_f32_32x32x16_bf16 v[48:63], v[32:35], v[64:67], 0
	s_waitcnt lgkmcnt(3)
	v_mfma_f32_32x32x16_bf16 v[32:47], v[36:39], v[64:67], 0
	v_mfma_f32_32x32x16_bf16 v[48:63], v[96:99], v[68:71], v[48:63]
	v_add3_u32 v96, v116, v164, v171
	v_add3_u32 v97, v116, v165, v171
	s_waitcnt lgkmcnt(2)
	v_mfma_f32_32x32x16_bf16 v[32:47], v[108:111], v[68:71], v[32:47]
	v_mfma_f32_32x32x16_bf16 v[48:63], v[100:103], v[72:75], v[48:63]
	s_waitcnt lgkmcnt(1)
	v_mfma_f32_32x32x16_bf16 v[32:47], v[112:115], v[72:75], v[32:47]
	v_mfma_f32_32x32x16_bf16 v[48:63], v[104:107], v[76:79], v[48:63]
	ds_read_b128 v[124:127], v96 offset:9216
	ds_read_b128 v[116:119], v96 offset:9248
	ds_read_b128 v[120:123], v97 offset:9216
	ds_read_b128 v[112:115], v97 offset:9248
	ds_read_b128 v[108:111], v96 offset:9280
	ds_read_b128 v[100:103], v96 offset:9312
	ds_read_b128 v[104:107], v97 offset:9280
	ds_read_b128 v[96:99], v97 offset:9312
	s_waitcnt lgkmcnt(8)
	v_mfma_f32_32x32x16_bf16 v[32:47], v[178:181], v[76:79], v[32:47]
	v_add_u32_e32 v128, s38, v162
	v_cmp_le_u32_e32 vcc, v128, v150
	v_cmp_gt_i32_e64 s[0:1], v128, v151
	s_and_b64 vcc, vcc, s[0:1]
	v_cndmask_b32_e32 v48, v172, v48, vcc
	v_cmp_lt_u32_e32 vcc, v128, v150
	v_cmp_ge_i32_e64 s[0:1], v128, v151
	s_and_b64 vcc, vcc, s[0:1]
	v_add_u32_e32 v177, 2, v128
	v_cndmask_b32_e32 v49, v172, v49, vcc
	v_cmp_le_u32_e32 vcc, v177, v150
	v_cmp_gt_i32_e64 s[0:1], v177, v151
	s_and_b64 vcc, vcc, s[0:1]
	v_add_u32_e32 v177, 3, v128
	v_cndmask_b32_e32 v50, v172, v50, vcc
	v_cmp_le_u32_e32 vcc, v177, v150
	v_cmp_gt_i32_e64 s[0:1], v177, v151
	s_and_b64 vcc, vcc, s[0:1]
	v_add_u32_e32 v177, 4, v128
	v_cndmask_b32_e32 v51, v172, v51, vcc
	v_cmp_le_u32_e32 vcc, v177, v150
	v_cmp_gt_i32_e64 s[0:1], v177, v151
	s_and_b64 vcc, vcc, s[0:1]
	v_add_u32_e32 v177, 5, v128
	v_cndmask_b32_e32 v52, v172, v52, vcc
	v_cmp_le_u32_e32 vcc, v177, v150
	v_cmp_gt_i32_e64 s[0:1], v177, v151
	s_and_b64 vcc, vcc, s[0:1]
	v_add_u32_e32 v177, 6, v128
	v_cndmask_b32_e32 v53, v172, v53, vcc
	v_cmp_le_u32_e32 vcc, v177, v150
	v_cmp_gt_i32_e64 s[0:1], v177, v151
	v_add_u32_e32 v177, s38, v161
	s_and_b64 vcc, vcc, s[0:1]
	v_or_b32_e32 v178, 7, v177
	v_cndmask_b32_e32 v54, v172, v54, vcc
	v_cmp_le_u32_e32 vcc, v178, v150
	v_cmp_gt_i32_e64 s[0:1], v178, v151
	s_and_b64 vcc, vcc, s[0:1]
	v_add_u32_e32 v178, 16, v128
	v_cndmask_b32_e32 v55, v172, v55, vcc
	v_cmp_le_u32_e32 vcc, v178, v150
	v_cmp_gt_i32_e64 s[0:1], v178, v151
	s_and_b64 vcc, vcc, s[0:1]
	v_add_u32_e32 v178, 17, v128
	v_cndmask_b32_e32 v56, v172, v56, vcc
	v_cmp_le_u32_e32 vcc, v178, v150
	v_cmp_gt_i32_e64 s[0:1], v178, v151
	s_and_b64 vcc, vcc, s[0:1]
	v_add_u32_e32 v178, 18, v128
	v_cndmask_b32_e32 v57, v172, v57, vcc
	v_cmp_le_u32_e32 vcc, v178, v150
	v_cmp_gt_i32_e64 s[0:1], v178, v151
	s_and_b64 vcc, vcc, s[0:1]
	v_add_u32_e32 v178, 19, v128
	v_cndmask_b32_e32 v58, v172, v58, vcc
	v_cmp_le_u32_e32 vcc, v178, v150
	v_cmp_gt_i32_e64 s[0:1], v178, v151
	s_and_b64 vcc, vcc, s[0:1]
	v_add_u32_e32 v178, 20, v128
	v_cndmask_b32_e32 v59, v172, v59, vcc
	v_cmp_le_u32_e32 vcc, v178, v150
	v_cmp_gt_i32_e64 s[0:1], v178, v151
	s_and_b64 vcc, vcc, s[0:1]
	v_add_u32_e32 v178, 21, v128
	v_cndmask_b32_e32 v60, v172, v60, vcc
	v_cmp_le_u32_e32 vcc, v178, v150
	v_cmp_gt_i32_e64 s[0:1], v178, v151
	s_and_b64 vcc, vcc, s[0:1]
	v_add_u32_e32 v178, 22, v128
	v_cndmask_b32_e32 v61, v172, v61, vcc
	v_cmp_le_u32_e32 vcc, v178, v150
	v_cmp_gt_i32_e64 s[0:1], v178, v151
	s_and_b64 vcc, vcc, s[0:1]
	v_or_b32_e32 v178, 23, v177
	v_cndmask_b32_e32 v62, v172, v62, vcc
	v_cmp_le_u32_e32 vcc, v178, v150
	v_cmp_gt_i32_e64 s[0:1], v178, v151
	s_and_b64 vcc, vcc, s[0:1]
	v_add_u32_e32 v178, 32, v128
	v_cndmask_b32_e32 v63, v172, v63, vcc
	v_cmp_le_u32_e32 vcc, v178, v150
	v_cmp_gt_i32_e64 s[0:1], v178, v151
	s_and_b64 vcc, vcc, s[0:1]
	v_cndmask_b32_e32 v178, v172, v32, vcc
	v_add_u32_e32 v32, 33, v128
	v_cmp_le_u32_e32 vcc, v32, v150
	v_cmp_gt_i32_e64 s[0:1], v32, v151
	s_and_b64 vcc, vcc, s[0:1]
	v_add_u32_e32 v32, 34, v128
	v_cndmask_b32_e32 v33, v172, v33, vcc
	v_cmp_le_u32_e32 vcc, v32, v150
	v_cmp_gt_i32_e64 s[0:1], v32, v151
	s_and_b64 vcc, vcc, s[0:1]
	v_add_u32_e32 v32, 35, v128
	v_cndmask_b32_e32 v34, v172, v34, vcc
	v_cmp_le_u32_e32 vcc, v32, v150
	v_cmp_gt_i32_e64 s[0:1], v32, v151
	s_and_b64 vcc, vcc, s[0:1]
	v_add_u32_e32 v32, 36, v128
	v_cndmask_b32_e32 v35, v172, v35, vcc
	v_cmp_le_u32_e32 vcc, v32, v150
	v_cmp_gt_i32_e64 s[0:1], v32, v151
	s_and_b64 vcc, vcc, s[0:1]
	v_add_u32_e32 v32, 37, v128
	v_cndmask_b32_e32 v36, v172, v36, vcc
	v_cmp_le_u32_e32 vcc, v32, v150
	v_cmp_gt_i32_e64 s[0:1], v32, v151
	s_and_b64 vcc, vcc, s[0:1]
	v_add_u32_e32 v32, 38, v128
	v_cndmask_b32_e32 v37, v172, v37, vcc
	v_cmp_le_u32_e32 vcc, v32, v150
	v_cmp_gt_i32_e64 s[0:1], v32, v151
	s_and_b64 vcc, vcc, s[0:1]
	v_or_b32_e32 v32, 39, v177
	v_cndmask_b32_e32 v38, v172, v38, vcc
	v_cmp_le_u32_e32 vcc, v32, v150
	v_cmp_gt_i32_e64 s[0:1], v32, v151
	s_and_b64 vcc, vcc, s[0:1]
	v_add_u32_e32 v32, 48, v128
	v_cndmask_b32_e32 v39, v172, v39, vcc
	v_cmp_le_u32_e32 vcc, v32, v150
	v_cmp_gt_i32_e64 s[0:1], v32, v151
	s_and_b64 vcc, vcc, s[0:1]
	v_add_u32_e32 v32, 49, v128
	v_cndmask_b32_e32 v179, v172, v40, vcc
; #define MFMA(a, b, c) __builtin_amdgcn_mfma_f32_32x32x16_bf16((a), (b), (c), 0, 0, 0)
; DI unsigned pack2(float a, float b) { f32x2_t v = {a, b}; bf16x2_t r = __builtin_convertvector(v, bf16x2_t); return __builtin_bit_cast(unsigned, r); }
; DI float fexp2(float x) { return __builtin_amdgcn_exp2f(x); }
; DI float shx(float v, int m) { return __shfl_xor(v, m, 64); }
; template <int DQK, bool MASKED, int MODE, class MF>
; DI void attn_step(const bf16_t* sK, const bf16_t* sVt, const bf16x8 (&qf)[DQK / 16], f32x16& o0, f32x16& o1, float& m, float& l,
;                   float sc, const MF& mf, int lane, f32x16 (&s)[2], float invl, bool lanevalid = true) {
;     ...
;       if (MASKED) { const int kk = sub * 32 + 16 * (q >> 3) + 8 * h + (q & 7); s[sub][q] = mf(kk) ? s[sub][q] : -3.0e38f; }
;       if (MODE != 2) mxr = fmaxf(mxr, s[sub][q]);
;     }
;   float alpha = 1.f;
;   if (MODE != 2) {
;     float mx = fmaxf(m, mxr * sc);
;     mx = fmaxf(mx, shx(mx, 32));
;     if (!MASKED) mx = lanevalid ? mx : m;
;     alpha = fexp2(m - mx);
;     m = mx;
;   }
;   const float moff = (!MASKED && !lanevalid) ? 1.0e30f : m;
;   float ps = 0.f;
; #pragma unroll
;   for (int sub = 0; sub < 2; ++sub)
; #pragma unroll
;     for (int q = 0; q < 16; ++q) {
;       float pv = fexp2(__builtin_fmaf(s[sub][q], sc, -moff));
;       if (MASKED && MODE != 0) pv = (s[sub][q] > -1.0e38f) ? pv : 0.f;
;       if (MODE == 2) pv *= invl;
;       s[sub][q] = pv;
;       ps += pv;
;     }
;   if (MODE != 2) {
;     ps += shx(ps, 32);
;     l = l * alpha + ps;
;   }
;   if (MODE == 1) return;
;   if (MODE == 0) {
; #pragma unroll
;     for (int q = 0; q < 16; ++q) { o0[q] *= alpha; o1[q] *= alpha; }
;   }
; #pragma unroll
;   for (int sub = 0; sub < 2; ++sub)
; #pragma unroll
;     for (int s2 = 0; s2 < 2; ++s2) {
;       union { bf16x8 v; unsigned u[4]; } pb;
; #pragma unroll
;       for (int e = 0; e < 4; ++e) pb.u[e] = pack2(s[sub][8 * s2 + 2 * e], s[sub][8 * s2 + 2 * e + 1]);
;       o0 = MFMA(vf[sub][s2][0], pb.v, o0);
;       o1 = MFMA(vf[sub][s2][1], pb.v, o1);
;     }
; }
	v_cmp_le_u32_e32 vcc, v32, v150
	v_cmp_gt_i32_e64 s[0:1], v32, v151
	s_and_b64 vcc, vcc, s[0:1]
	v_add_u32_e32 v32, 50, v128
	v_cndmask_b32_e32 v41, v172, v41, vcc
	v_cmp_le_u32_e32 vcc, v32, v150
	v_cmp_gt_i32_e64 s[0:1], v32, v151
	s_and_b64 vcc, vcc, s[0:1]
	v_add_u32_e32 v32, 51, v128
	v_cndmask_b32_e32 v42, v172, v42, vcc
	v_cmp_le_u32_e32 vcc, v32, v150
	v_cmp_gt_i32_e64 s[0:1], v32, v151
	s_and_b64 vcc, vcc, s[0:1]
	v_add_u32_e32 v32, 52, v128
	v_cndmask_b32_e32 v43, v172, v43, vcc
	v_cmp_le_u32_e32 vcc, v32, v150
	v_cmp_gt_i32_e64 s[0:1], v32, v151
	s_and_b64 vcc, vcc, s[0:1]
	v_add_u32_e32 v32, 53, v128
	v_cndmask_b32_e32 v44, v172, v44, vcc
	v_cmp_le_u32_e32 vcc, v32, v150
	v_cmp_gt_i32_e64 s[0:1], v32, v151
	s_and_b64 vcc, vcc, s[0:1]
	v_add_u32_e32 v32, 54, v128
	v_cndmask_b32_e32 v45, v172, v45, vcc
	v_cmp_le_u32_e32 vcc, v32, v150
	v_cmp_gt_i32_e64 s[0:1], v32, v151
	s_and_b64 vcc, vcc, s[0:1]
	v_or_b32_e32 v32, 55, v177
	v_cndmask_b32_e32 v46, v172, v46, vcc
	v_cmp_le_u32_e32 vcc, v32, v150
	v_cmp_gt_i32_e64 s[0:1], v32, v151
	v_max3_f32 v32, v48, s43, v49
	v_max3_f32 v32, v32, v50, v51
	v_max3_f32 v32, v32, v52, v53
	v_max3_f32 v32, v32, v54, v55
	v_max3_f32 v32, v32, v56, v57
	v_max3_f32 v32, v32, v58, v59
	v_max3_f32 v32, v32, v60, v61
	v_max3_f32 v32, v32, v62, v63
	v_max3_f32 v32, v32, v178, v33
	v_max3_f32 v32, v32, v34, v35
	v_max3_f32 v32, v32, v36, v37
	v_max3_f32 v32, v32, v38, v39
	v_max3_f32 v32, v32, v179, v41
	s_and_b64 vcc, vcc, s[0:1]
	v_max3_f32 v32, v32, v42, v43
	v_cndmask_b32_e32 v47, v172, v47, vcc
	v_max3_f32 v32, v32, v44, v45
	v_max3_f32 v32, v32, v46, v47
	v_mul_f32_e32 v32, 0x3e38aa3b, v32
	v_max_f32_e32 v40, v176, v176
	v_max_f32_e32 v32, v40, v32
	ds_bpermute_b32 v40, v174, v32
	s_add_i32 s47, s47, 1
	s_add_i32 s0, s46, s47
	s_add_i32 s38, s38, 64
	s_add_i32 s0, s0, -1
	s_waitcnt lgkmcnt(0)
	v_max_f32_e32 v40, v40, v40
	v_max_f32_e32 v32, v32, v40
	v_fma_f32 v40, v48, s44, -v32
	v_exp_f32_e32 v48, v40
	v_fma_f32 v49, v49, s44, -v32
	v_exp_f32_e32 v49, v49
	v_fma_f32 v50, v50, s44, -v32
	v_exp_f32_e32 v50, v50
	v_fma_f32 v51, v51, s44, -v32
	v_exp_f32_e32 v51, v51
	v_fma_f32 v52, v52, s44, -v32
	v_add_f32_e32 v128, 0, v48
	v_exp_f32_e32 v52, v52
	v_fma_f32 v53, v53, s44, -v32
	v_add_f32_e32 v128, v49, v128
	v_exp_f32_e32 v53, v53
	v_fma_f32 v54, v54, s44, -v32
	v_add_f32_e32 v128, v50, v128
	v_exp_f32_e32 v54, v54
	v_fma_f32 v55, v55, s44, -v32
	v_add_f32_e32 v128, v51, v128
	v_exp_f32_e32 v55, v55
	v_fma_f32 v56, v56, s44, -v32
	v_add_f32_e32 v128, v52, v128
	v_exp_f32_e32 v56, v56
	v_fma_f32 v57, v57, s44, -v32
	v_add_f32_e32 v128, v53, v128
	v_exp_f32_e32 v57, v57
	v_fma_f32 v58, v58, s44, -v32
	v_add_f32_e32 v128, v54, v128
	v_exp_f32_e32 v58, v58
	v_fma_f32 v59, v59, s44, -v32
	v_add_f32_e32 v128, v55, v128
	v_exp_f32_e32 v59, v59
	v_fma_f32 v60, v60, s44, -v32
	v_add_f32_e32 v128, v56, v128
	v_exp_f32_e32 v60, v60
	v_fma_f32 v61, v61, s44, -v32
	v_add_f32_e32 v128, v57, v128
	v_exp_f32_e32 v61, v61
	v_fma_f32 v62, v62, s44, -v32
	v_add_f32_e32 v128, v58, v128
	v_exp_f32_e32 v62, v62
	v_fma_f32 v63, v63, s44, -v32
	v_sub_f32_e32 v40, v176, v32
	v_add_f32_e32 v128, v59, v128
	v_exp_f32_e32 v63, v63
	v_fma_f32 v176, v178, s44, -v32
	v_add_f32_e32 v128, v60, v128
	v_exp_f32_e32 v176, v176
	v_fma_f32 v33, v33, s44, -v32
	v_add_f32_e32 v128, v61, v128
	v_exp_f32_e32 v33, v33
	v_fma_f32 v34, v34, s44, -v32
	v_add_f32_e32 v128, v62, v128
	v_exp_f32_e32 v177, v34
	v_fma_f32 v34, v35, s44, -v32
	v_add_f32_e32 v128, v63, v128
	v_exp_f32_e32 v178, v34
	v_fma_f32 v34, v36, s44, -v32
	v_add_f32_e32 v128, v176, v128
	v_exp_f32_e32 v180, v34
	v_fma_f32 v35, v37, s44, -v32
	v_add_f32_e32 v34, v33, v128
	v_exp_f32_e32 v128, v35
	v_fma_f32 v35, v38, s44, -v32
	v_add_f32_e32 v34, v177, v34
	v_exp_f32_e32 v38, v35
	v_fma_f32 v35, v39, s44, -v32
	v_add_f32_e32 v34, v178, v34
	v_exp_f32_e32 v39, v35
	v_add_f32_e32 v34, v180, v34
	v_exp_f32_e32 v40, v40
	v_add_f32_e32 v34, v128, v34
	v_add_f32_e32 v34, v38, v34
	v_add_f32_e32 v181, v39, v34
	v_fma_f32 v34, v179, s44, -v32
	v_exp_f32_e32 v179, v34
	v_pk_mul_f32 v[14:15], v[14:15], v[40:41] op_sel_hi:[1,0]
	v_pk_mul_f32 v[12:13], v[12:13], v[40:41] op_sel_hi:[1,0]
	v_pk_mul_f32 v[10:11], v[10:11], v[40:41] op_sel_hi:[1,0]
	v_pk_mul_f32 v[8:9], v[8:9], v[40:41] op_sel_hi:[1,0]
	v_pk_mul_f32 v[6:7], v[6:7], v[40:41] op_sel_hi:[1,0]
	v_pk_mul_f32 v[4:5], v[4:5], v[40:41] op_sel_hi:[1,0]
	v_pk_mul_f32 v[2:3], v[2:3], v[40:41] op_sel_hi:[1,0]
	v_pk_mul_f32 v[0:1], v[0:1], v[40:41] op_sel_hi:[1,0]
	v_pk_mul_f32 v[30:31], v[30:31], v[40:41] op_sel_hi:[1,0]
	v_cvt_pk_bf16_f32 v34, v48, v49
	v_cvt_pk_bf16_f32 v35, v50, v51
	v_cvt_pk_bf16_f32 v36, v52, v53
	v_cvt_pk_bf16_f32 v37, v54, v55
	v_pk_mul_f32 v[28:29], v[28:29], v[40:41] op_sel_hi:[1,0]
	v_pk_mul_f32 v[26:27], v[26:27], v[40:41] op_sel_hi:[1,0]
	v_pk_mul_f32 v[24:25], v[24:25], v[40:41] op_sel_hi:[1,0]
	v_pk_mul_f32 v[22:23], v[22:23], v[40:41] op_sel_hi:[1,0]
	v_pk_mul_f32 v[20:21], v[20:21], v[40:41] op_sel_hi:[1,0]
	v_pk_mul_f32 v[18:19], v[18:19], v[40:41] op_sel_hi:[1,0]
	v_pk_mul_f32 v[16:17], v[16:17], v[40:41] op_sel_hi:[1,0]
	v_mfma_f32_32x32x16_bf16 v[0:15], v[124:127], v[34:37], v[0:15]
	v_fma_f32 v42, v42, s44, -v32
	v_exp_f32_e32 v42, v42
	v_fma_f32 v43, v43, s44, -v32
	v_exp_f32_e32 v43, v43
	v_fma_f32 v44, v44, s44, -v32
	v_add_f32_e32 v48, v179, v181
	v_exp_f32_e32 v44, v44
	v_mfma_f32_32x32x16_bf16 v[16:31], v[120:123], v[34:37], v[16:31]
	v_fma_f32 v34, v41, s44, -v32
	v_exp_f32_e32 v41, v34
	v_cvt_pk_bf16_f32 v34, v56, v57
	v_cvt_pk_bf16_f32 v35, v58, v59
	v_cvt_pk_bf16_f32 v36, v60, v61
	v_cvt_pk_bf16_f32 v37, v62, v63
	v_add_f32_e32 v48, v41, v48
	s_cmp_ge_u32 s0, s41
	v_mfma_f32_32x32x16_bf16 v[0:15], v[116:119], v[34:37], v[0:15]
	v_mfma_f32_32x32x16_bf16 v[16:31], v[112:115], v[34:37], v[16:31]
	v_add_f32_e32 v34, v42, v48
	v_add_f32_e32 v34, v43, v34
	v_add_f32_e32 v48, v44, v34
	v_cvt_pk_bf16_f32 v34, v176, v33
	v_cvt_pk_bf16_f32 v35, v177, v178
	v_cvt_pk_bf16_f32 v36, v180, v128
	v_cvt_pk_bf16_f32 v37, v38, v39
	v_fma_f32 v33, v45, s44, -v32
	v_fma_f32 v38, v46, s44, -v32
	v_mfma_f32_32x32x16_bf16 v[0:15], v[108:111], v[34:37], v[0:15]
	v_exp_f32_e32 v33, v33
	v_exp_f32_e32 v39, v38
	v_fma_f32 v38, v47, s44, -v32
	v_exp_f32_e32 v45, v38
	v_add_f32_e32 v38, v33, v48
	v_mfma_f32_32x32x16_bf16 v[16:31], v[104:107], v[34:37], v[16:31]
	v_add_f32_e32 v34, v39, v38
	v_cvt_pk_bf16_f32 v36, v179, v41
	v_cvt_pk_bf16_f32 v37, v42, v43
	v_cvt_pk_bf16_f32 v38, v44, v33
	v_cvt_pk_bf16_f32 v39, v39, v45
	v_add_f32_e32 v34, v45, v34
	ds_bpermute_b32 v35, v174, v34
	v_mfma_f32_32x32x16_bf16 v[0:15], v[100:103], v[36:39], v[0:15]
	s_waitcnt lgkmcnt(0)
	v_add_f32_e32 v34, v34, v35
	v_fmac_f32_e32 v34, v175, v40
	v_mfma_f32_32x32x16_bf16 v[16:31], v[96:99], v[36:39], v[16:31]
	s_cbranch_scc1 .LBB0_337
	v_mov_b32_e32 v175, v34
	v_mov_b32_e32 v176, v32
	s_branch .LBB0_346

; DI void phase_attn_swa(const Params& P, const float* sinks, bf16_t* og, unsigned char* smem, int L, int G) {
;     ...
;     int qt, bg; gqa_item(it, L, G, gi, qt, bg);
;     const int b = bg >> 2, g = bg & 3;
;     const int t0 = qt * 32, t = t0 + r, head = g * 4 + w;
;     const size_t tok = (size_t)b * SEQ + t;
;     bf16x8 qf[4];
; #pragma unroll
;     for (int ks = 0; ks < 4; ++ks) qf[ks] = *(const bf16x8*)(big + SW_Q + tok * 1024 + head * 64 + ks * 16 + 8 * h);
;     f32x16 o0, o1, s[2]; o_zero(o0, o1);
;     float m = sinks[head] * LOG2E, l = 1.f;
;     const bf16_t* kb = big + SW_K + (size_t)b * SEQ * 256 + g * 64;
;     const bf16_t* vb = big + SW_VT + (size_t)((b * 4 + g) * 64) * SEQ;
;     const int jlo = (t0 - 127 > 0 ? t0 - 127 : 0) >> 6, jhi = (t0 + 31) >> 6;
;     KVR R; kv64_fetch(R, kb, 256, vb, SEQ, jlo * 64, true, tid);
;     __syncthreads();
;     kv64_store(R, sK, sVt, tid);
;     if (jlo < jhi) kv64_fetch(R, kb, 256, vb, SEQ, jlo * 64 + 64, true, tid);
.LBB0_1664:
	v_ashrrev_i32_e32 v0, 2, v2
	s_lshl_b32 s10, s11, 5
	v_ashrrev_i32_e32 v1, 31, v0
	v_or_b32_e32 v150, s10, v135
	v_lshlrev_b64 v[148:149], 11, v[0:1]
	v_mov_b32_e32 v151, v129
	v_and_b32_e32 v3, 3, v2
	v_lshl_add_u64 v[4:5], v[148:149], 0, v[150:151]
	v_lshl_or_b32 v173, v3, 2, v133
	v_lshlrev_b64 v[4:5], 11, v[4:5]
	s_max_i32 s0, s10, 0x7f
	v_lshl_add_u64 v[4:5], s[76:77], 0, v[4:5]
	v_lshlrev_b32_e32 v128, 7, v173
	v_lshlrev_b64 v[0:1], 20, v[0:1]
	v_lshlrev_b32_e32 v2, 6, v2
	s_add_i32 s17, s0, 0xffffff81
	v_lshl_add_u64 v[4:5], v[4:5], 0, v[128:129]
	v_lshl_add_u64 v[0:1], s[66:67], 0, v[0:1]
	v_lshlrev_b32_e32 v128, 7, v3
	v_ashrrev_i32_e32 v3, 31, v2
	s_and_b32 s8, s17, 0xffffffc0
	v_lshl_add_u64 v[12:13], v[4:5], 0, v[140:141]
	v_lshlrev_b32_e32 v4, 2, v173
	v_lshl_add_u64 v[0:1], v[0:1], 0, v[128:129]
	v_lshlrev_b64 v[2:3], 12, v[2:3]
	v_or_b32_e32 v128, s8, v158
	global_load_dwordx4 v[64:67], v[12:13], off
	global_load_dwordx4 v[68:71], v[12:13], off offset:32
	global_load_dword v10, v4, s[92:93]
	v_lshl_add_u64 v[4:5], s[4:5], 0, v[2:3]
	v_lshlrev_b64 v[2:3], 9, v[128:129]
	v_or_b32_e32 v128, s8, v159
	v_lshl_add_u64 v[2:3], v[0:1], 0, v[2:3]
	v_lshlrev_b64 v[6:7], 9, v[128:129]
	v_lshl_add_u64 v[2:3], v[2:3], 0, v[142:143]
	v_lshl_add_u64 v[6:7], v[0:1], 0, v[6:7]
	v_lshl_add_u64 v[6:7], v[6:7], 0, v[142:143]
	global_load_dwordx4 v[80:83], v[2:3], off
	global_load_dwordx4 v[84:87], v[6:7], off
	v_lshl_add_u64 v[2:3], v[4:5], 0, v[144:145]
	s_lshl_b64 s[0:1], s[8:9], 1
	v_lshl_add_u64 v[6:7], v[2:3], 0, s[0:1]
	v_lshl_add_u64 v[6:7], v[6:7], 0, v[142:143]
	v_lshl_add_u64 v[4:5], v[4:5], 0, v[146:147]
	global_load_dwordx4 v[88:91], v[6:7], off
	v_lshl_add_u64 v[8:9], v[4:5], 0, s[0:1]
	v_lshl_add_u64 v[8:9], v[8:9], 0, v[142:143]
	global_load_dwordx4 v[92:95], v[8:9], off
	global_load_dwordx4 v[72:75], v[12:13], off offset:64
	global_load_dwordx4 v[76:79], v[12:13], off offset:96
	s_lshr_b32 s11, s11, 1
	s_lshr_b32 s17, s17, 6
	s_cmp_ge_u32 s17, s11
	s_barrier
	s_waitcnt vmcnt(3)
	ds_write_b128 v160, v[88:91] offset:9216
	ds_write_b128 v160, v[80:83]
	ds_write_b128 v160, v[84:87] offset:4608
	s_waitcnt vmcnt(2)
	ds_write_b128 v160, v[92:95] offset:13824
	s_waitcnt vmcnt(0)
	s_cbranch_scc1 .LBB0_1666
	s_add_i32 s0, s8, 64
	v_or_b32_e32 v128, s0, v158
	v_lshlrev_b64 v[12:13], 9, v[128:129]
	v_or_b32_e32 v128, s0, v159
	v_lshl_add_u64 v[12:13], v[0:1], 0, v[12:13]
	v_lshlrev_b64 v[14:15], 9, v[128:129]
	v_lshl_add_u64 v[12:13], v[12:13], 0, v[142:143]
	v_lshl_add_u64 v[14:15], v[0:1], 0, v[14:15]
	v_lshl_add_u64 v[14:15], v[14:15], 0, v[142:143]
	global_load_dwordx4 v[80:83], v[12:13], off
	global_load_dwordx4 v[84:87], v[14:15], off
	global_load_dwordx4 v[88:91], v[6:7], off offset:128
	global_load_dwordx4 v[92:95], v[8:9], off offset:128

; #define MFMA(a, b, c) __builtin_amdgcn_mfma_f32_32x32x16_bf16((a), (b), (c), 0, 0, 0)
; template <int DQK, bool MASKED, int MODE, class MF>
; DI void attn_step(const bf16_t* sK, const bf16_t* sVt, const bf16x8 (&qf)[DQK / 16], f32x16& o0, f32x16& o1, float& m, float& l,
;                   float sc, const MF& mf, int lane, f32x16 (&s)[2], float invl, bool lanevalid = true) {
;     ...
;   bf16x8 kf[2][DQK / 16];
; #pragma unroll
;   for (int sub = 0; sub < 2; ++sub)
; #pragma unroll
;     for (int ks = 0; ks < DQK / 16; ++ks) kf[sub][ks] = *(const bf16x8*)(sK + (sub * 32 + pr) * KST + ks * 16 + 8 * h);
;   __builtin_amdgcn_sched_barrier(0);
; #pragma unroll
;   for (int q = 0; q < 16; ++q) { s[0][q] = 0.f; s[1][q] = 0.f; }
; #pragma unroll
;   for (int ks = 0; ks < DQK / 16; ++ks) {
;     s[0] = MFMA(kf[0][ks], qf[ks], s[0]);
;     s[1] = MFMA(kf[1][ks], qf[ks], s[1]);
;   }
;   bf16x8 vf[2][2][2];
;   if (MODE != 1) {
; #pragma unroll
;     for (int sub = 0; sub < 2; ++sub)
; #pragma unroll
;       for (int s2 = 0; s2 < 2; ++s2) {
;         vf[sub][s2][0] = *(const bf16x8*)(sVt + r * 72 + sub * 32 + s2 * 16 + 8 * h);
;         vf[sub][s2][1] = *(const bf16x8*)(sVt + (32 + r) * 72 + sub * 32 + s2 * 16 + 8 * h);
;       }
;     __builtin_amdgcn_sched_barrier(0);
;   }
;   float mxr = -3.0e38f;
; #pragma unroll
;   for (int sub = 0; sub < 2; ++sub)
; #pragma unroll
;     for (int q = 0; q < 16; ++q) {
;       if (MASKED) { const int kk = sub * 32 + 16 * (q >> 3) + 8 * h + (q & 7); s[sub][q] = mf(kk) ? s[sub][q] : -3.0e38f; }
;       if (MODE != 2) mxr = fmaxf(mxr, s[sub][q]);
.LBB0_1672:
	s_mulk_i32 s0, 0x4800
	v_add_u32_e32 v40, s0, v163
	ds_read_b128 v[32:35], v40
	ds_read_b128 v[96:99], v40 offset:32
	ds_read_b128 v[100:103], v40 offset:64
	ds_read_b128 v[104:107], v40 offset:96
	ds_read_b128 v[36:39], v40 offset:4608
	ds_read_b128 v[108:111], v40 offset:4640
	ds_read_b128 v[112:115], v40 offset:4672
	ds_read_b128 v[178:181], v40 offset:4704
	v_add_u32_e32 v116, s0, v137
	s_waitcnt lgkmcnt(7)
	v_mfma_f32_32x32x16_bf16 v[48:63], v[32:35], v[64:67], 0
	s_waitcnt lgkmcnt(3)
	v_mfma_f32_32x32x16_bf16 v[32:47], v[36:39], v[64:67], 0
	v_mfma_f32_32x32x16_bf16 v[48:63], v[96:99], v[68:71], v[48:63]
	v_add3_u32 v96, v116, v164, v171
	v_add3_u32 v97, v116, v165, v171
	s_waitcnt lgkmcnt(2)
	v_mfma_f32_32x32x16_bf16 v[32:47], v[108:111], v[68:71], v[32:47]
	v_mfma_f32_32x32x16_bf16 v[48:63], v[100:103], v[72:75], v[48:63]
	s_waitcnt lgkmcnt(1)
	v_mfma_f32_32x32x16_bf16 v[32:47], v[112:115], v[72:75], v[32:47]
	v_mfma_f32_32x32x16_bf16 v[48:63], v[104:107], v[76:79], v[48:63]
	ds_read_b128 v[124:127], v96 offset:9216
	ds_read_b128 v[116:119], v96 offset:9248
	ds_read_b128 v[120:123], v97 offset:9216
	ds_read_b128 v[112:115], v97 offset:9248
	ds_read_b128 v[108:111], v96 offset:9280
	ds_read_b128 v[100:103], v96 offset:9312
	ds_read_b128 v[104:107], v97 offset:9280
	ds_read_b128 v[96:99], v97 offset:9312
	s_waitcnt lgkmcnt(8)
	v_mfma_f32_32x32x16_bf16 v[32:47], v[178:181], v[76:79], v[32:47]
	v_add_u32_e32 v128, s8, v162
	v_cmp_le_u32_e32 vcc, v128, v150
	v_cmp_gt_i32_e64 s[0:1], v128, v151
	s_and_b64 vcc, vcc, s[0:1]
	v_cndmask_b32_e32 v48, v172, v48, vcc
	v_cmp_lt_u32_e32 vcc, v128, v150
	v_cmp_ge_i32_e64 s[0:1], v128, v151
	s_and_b64 vcc, vcc, s[0:1]
	v_add_u32_e32 v177, 2, v128
	v_cndmask_b32_e32 v49, v172, v49, vcc
	v_cmp_le_u32_e32 vcc, v177, v150
	v_cmp_gt_i32_e64 s[0:1], v177, v151
	s_and_b64 vcc, vcc, s[0:1]
	v_add_u32_e32 v177, 3, v128
	v_cndmask_b32_e32 v50, v172, v50, vcc
	v_cmp_le_u32_e32 vcc, v177, v150
	v_cmp_gt_i32_e64 s[0:1], v177, v151
	s_and_b64 vcc, vcc, s[0:1]
	v_add_u32_e32 v177, 4, v128
	v_cndmask_b32_e32 v51, v172, v51, vcc
	v_cmp_le_u32_e32 vcc, v177, v150
	v_cmp_gt_i32_e64 s[0:1], v177, v151
	s_and_b64 vcc, vcc, s[0:1]
	v_add_u32_e32 v177, 5, v128
	v_cndmask_b32_e32 v52, v172, v52, vcc
	v_cmp_le_u32_e32 vcc, v177, v150
	v_cmp_gt_i32_e64 s[0:1], v177, v151
	s_and_b64 vcc, vcc, s[0:1]
	v_add_u32_e32 v177, 6, v128
	v_cndmask_b32_e32 v53, v172, v53, vcc
	v_cmp_le_u32_e32 vcc, v177, v150
	v_cmp_gt_i32_e64 s[0:1], v177, v151
	v_add_u32_e32 v177, s8, v161
	s_and_b64 vcc, vcc, s[0:1]
	v_or_b32_e32 v178, 7, v177
	v_cndmask_b32_e32 v54, v172, v54, vcc
	v_cmp_le_u32_e32 vcc, v178, v150
	v_cmp_gt_i32_e64 s[0:1], v178, v151
	s_and_b64 vcc, vcc, s[0:1]
	v_add_u32_e32 v178, 16, v128
	v_cndmask_b32_e32 v55, v172, v55, vcc
	v_cmp_le_u32_e32 vcc, v178, v150
	v_cmp_gt_i32_e64 s[0:1], v178, v151
	s_and_b64 vcc, vcc, s[0:1]
	v_add_u32_e32 v178, 17, v128
	v_cndmask_b32_e32 v56, v172, v56, vcc
	v_cmp_le_u32_e32 vcc, v178, v150
	v_cmp_gt_i32_e64 s[0:1], v178, v151
	s_and_b64 vcc, vcc, s[0:1]
	v_add_u32_e32 v178, 18, v128
	v_cndmask_b32_e32 v57, v172, v57, vcc
	v_cmp_le_u32_e32 vcc, v178, v150
	v_cmp_gt_i32_e64 s[0:1], v178, v151
	s_and_b64 vcc, vcc, s[0:1]
	v_add_u32_e32 v178, 19, v128
	v_cndmask_b32_e32 v58, v172, v58, vcc
	v_cmp_le_u32_e32 vcc, v178, v150
	v_cmp_gt_i32_e64 s[0:1], v178, v151
	s_and_b64 vcc, vcc, s[0:1]
	v_add_u32_e32 v178, 20, v128
	v_cndmask_b32_e32 v59, v172, v59, vcc
	v_cmp_le_u32_e32 vcc, v178, v150
	v_cmp_gt_i32_e64 s[0:1], v178, v151
	s_and_b64 vcc, vcc, s[0:1]
	v_add_u32_e32 v178, 21, v128
	v_cndmask_b32_e32 v60, v172, v60, vcc
	v_cmp_le_u32_e32 vcc, v178, v150
	v_cmp_gt_i32_e64 s[0:1], v178, v151
	s_and_b64 vcc, vcc, s[0:1]
	v_add_u32_e32 v178, 22, v128
	v_cndmask_b32_e32 v61, v172, v61, vcc
	v_cmp_le_u32_e32 vcc, v178, v150
	v_cmp_gt_i32_e64 s[0:1], v178, v151
	s_and_b64 vcc, vcc, s[0:1]
	v_or_b32_e32 v178, 23, v177
	v_cndmask_b32_e32 v62, v172, v62, vcc
	v_cmp_le_u32_e32 vcc, v178, v150
	v_cmp_gt_i32_e64 s[0:1], v178, v151
	s_and_b64 vcc, vcc, s[0:1]
	v_add_u32_e32 v178, 32, v128
	v_cndmask_b32_e32 v63, v172, v63, vcc
	v_cmp_le_u32_e32 vcc, v178, v150
	v_cmp_gt_i32_e64 s[0:1], v178, v151
	s_and_b64 vcc, vcc, s[0:1]
	v_cndmask_b32_e32 v178, v172, v32, vcc
	v_add_u32_e32 v32, 33, v128
	v_cmp_le_u32_e32 vcc, v32, v150
	v_cmp_gt_i32_e64 s[0:1], v32, v151
	s_and_b64 vcc, vcc, s[0:1]
	v_add_u32_e32 v32, 34, v128
	v_cndmask_b32_e32 v33, v172, v33, vcc
	v_cmp_le_u32_e32 vcc, v32, v150
	v_cmp_gt_i32_e64 s[0:1], v32, v151
	s_and_b64 vcc, vcc, s[0:1]
	v_add_u32_e32 v32, 35, v128
	v_cndmask_b32_e32 v34, v172, v34, vcc
	v_cmp_le_u32_e32 vcc, v32, v150
	v_cmp_gt_i32_e64 s[0:1], v32, v151
	s_and_b64 vcc, vcc, s[0:1]
	v_add_u32_e32 v32, 36, v128
	v_cndmask_b32_e32 v35, v172, v35, vcc
	v_cmp_le_u32_e32 vcc, v32, v150
	v_cmp_gt_i32_e64 s[0:1], v32, v151
	s_and_b64 vcc, vcc, s[0:1]
	v_add_u32_e32 v32, 37, v128
	v_cndmask_b32_e32 v36, v172, v36, vcc
	v_cmp_le_u32_e32 vcc, v32, v150
	v_cmp_gt_i32_e64 s[0:1], v32, v151
	s_and_b64 vcc, vcc, s[0:1]
	v_add_u32_e32 v32, 38, v128
	v_cndmask_b32_e32 v37, v172, v37, vcc
	v_cmp_le_u32_e32 vcc, v32, v150
	v_cmp_gt_i32_e64 s[0:1], v32, v151
	s_and_b64 vcc, vcc, s[0:1]
	v_or_b32_e32 v32, 39, v177
	v_cndmask_b32_e32 v38, v172, v38, vcc
	v_cmp_le_u32_e32 vcc, v32, v150
	v_cmp_gt_i32_e64 s[0:1], v32, v151
	s_and_b64 vcc, vcc, s[0:1]
	v_add_u32_e32 v32, 48, v128
	v_cndmask_b32_e32 v39, v172, v39, vcc
	v_cmp_le_u32_e32 vcc, v32, v150
	v_cmp_gt_i32_e64 s[0:1], v32, v151
	s_and_b64 vcc, vcc, s[0:1]
	v_add_u32_e32 v32, 49, v128
	v_cndmask_b32_e32 v179, v172, v40, vcc
; #define MFMA(a, b, c) __builtin_amdgcn_mfma_f32_32x32x16_bf16((a), (b), (c), 0, 0, 0)
; DI unsigned pack2(float a, float b) { f32x2_t v = {a, b}; bf16x2_t r = __builtin_convertvector(v, bf16x2_t); return __builtin_bit_cast(unsigned, r); }
; DI float fexp2(float x) { return __builtin_amdgcn_exp2f(x); }
; DI float shx(float v, int m) { return __shfl_xor(v, m, 64); }
; template <int DQK, bool MASKED, int MODE, class MF>
; DI void attn_step(const bf16_t* sK, const bf16_t* sVt, const bf16x8 (&qf)[DQK / 16], f32x16& o0, f32x16& o1, float& m, float& l,
;                   float sc, const MF& mf, int lane, f32x16 (&s)[2], float invl, bool lanevalid = true) {
;     ...
;       if (MASKED) { const int kk = sub * 32 + 16 * (q >> 3) + 8 * h + (q & 7); s[sub][q] = mf(kk) ? s[sub][q] : -3.0e38f; }
;       if (MODE != 2) mxr = fmaxf(mxr, s[sub][q]);
;     }
;   float alpha = 1.f;
;   if (MODE != 2) {
;     float mx = fmaxf(m, mxr * sc);
;     mx = fmaxf(mx, shx(mx, 32));
;     if (!MASKED) mx = lanevalid ? mx : m;
;     alpha = fexp2(m - mx);
;     m = mx;
;   }
;   const float moff = (!MASKED && !lanevalid) ? 1.0e30f : m;
;   float ps = 0.f;
; #pragma unroll
;   for (int sub = 0; sub < 2; ++sub)
; #pragma unroll
;     for (int q = 0; q < 16; ++q) {
;       float pv = fexp2(__builtin_fmaf(s[sub][q], sc, -moff));
;       if (MASKED && MODE != 0) pv = (s[sub][q] > -1.0e38f) ? pv : 0.f;
;       if (MODE == 2) pv *= invl;
;       s[sub][q] = pv;
;       ps += pv;
;     }
;   if (MODE != 2) {
;     ps += shx(ps, 32);
;     l = l * alpha + ps;
;   }
;   if (MODE == 1) return;
;   if (MODE == 0) {
; #pragma unroll
;     for (int q = 0; q < 16; ++q) { o0[q] *= alpha; o1[q] *= alpha; }
;   }
; #pragma unroll
;   for (int sub = 0; sub < 2; ++sub)
; #pragma unroll
;     for (int s2 = 0; s2 < 2; ++s2) {
;       union { bf16x8 v; unsigned u[4]; } pb;
; #pragma unroll
;       for (int e = 0; e < 4; ++e) pb.u[e] = pack2(s[sub][8 * s2 + 2 * e], s[sub][8 * s2 + 2 * e + 1]);
;       o0 = MFMA(vf[sub][s2][0], pb.v, o0);
;       o1 = MFMA(vf[sub][s2][1], pb.v, o1);
;     }
; }
	v_cmp_le_u32_e32 vcc, v32, v150
	v_cmp_gt_i32_e64 s[0:1], v32, v151
	s_and_b64 vcc, vcc, s[0:1]
	v_add_u32_e32 v32, 50, v128
	v_cndmask_b32_e32 v41, v172, v41, vcc
	v_cmp_le_u32_e32 vcc, v32, v150
	v_cmp_gt_i32_e64 s[0:1], v32, v151
	s_and_b64 vcc, vcc, s[0:1]
	v_add_u32_e32 v32, 51, v128
	v_cndmask_b32_e32 v42, v172, v42, vcc
	v_cmp_le_u32_e32 vcc, v32, v150
	v_cmp_gt_i32_e64 s[0:1], v32, v151
	s_and_b64 vcc, vcc, s[0:1]
	v_add_u32_e32 v32, 52, v128
	v_cndmask_b32_e32 v43, v172, v43, vcc
	v_cmp_le_u32_e32 vcc, v32, v150
	v_cmp_gt_i32_e64 s[0:1], v32, v151
	s_and_b64 vcc, vcc, s[0:1]
	v_add_u32_e32 v32, 53, v128
	v_cndmask_b32_e32 v44, v172, v44, vcc
	v_cmp_le_u32_e32 vcc, v32, v150
	v_cmp_gt_i32_e64 s[0:1], v32, v151
	s_and_b64 vcc, vcc, s[0:1]
	v_add_u32_e32 v32, 54, v128
	v_cndmask_b32_e32 v45, v172, v45, vcc
	v_cmp_le_u32_e32 vcc, v32, v150
	v_cmp_gt_i32_e64 s[0:1], v32, v151
	s_and_b64 vcc, vcc, s[0:1]
	v_or_b32_e32 v32, 55, v177
	v_cndmask_b32_e32 v46, v172, v46, vcc
	v_cmp_le_u32_e32 vcc, v32, v150
	v_cmp_gt_i32_e64 s[0:1], v32, v151
	v_max3_f32 v32, v48, s14, v49
	v_max3_f32 v32, v32, v50, v51
	v_max3_f32 v32, v32, v52, v53
	v_max3_f32 v32, v32, v54, v55
	v_max3_f32 v32, v32, v56, v57
	v_max3_f32 v32, v32, v58, v59
	v_max3_f32 v32, v32, v60, v61
	v_max3_f32 v32, v32, v62, v63
	v_max3_f32 v32, v32, v178, v33
	v_max3_f32 v32, v32, v34, v35
	v_max3_f32 v32, v32, v36, v37
	v_max3_f32 v32, v32, v38, v39
	v_max3_f32 v32, v32, v179, v41
	s_and_b64 vcc, vcc, s[0:1]
	v_max3_f32 v32, v32, v42, v43
	v_cndmask_b32_e32 v47, v172, v47, vcc
	v_max3_f32 v32, v32, v44, v45
	v_max3_f32 v32, v32, v46, v47
	v_mul_f32_e32 v32, 0x3e38aa3b, v32
	v_max_f32_e32 v40, v176, v176
	v_max_f32_e32 v32, v40, v32
	ds_bpermute_b32 v40, v174, v32
	s_add_i32 s18, s18, 1
	s_add_i32 s0, s17, s18
	s_add_i32 s8, s8, 64
	s_add_i32 s0, s0, -1
	s_waitcnt lgkmcnt(0)
	v_max_f32_e32 v40, v40, v40
	v_max_f32_e32 v32, v32, v40
	v_fma_f32 v40, v48, s15, -v32
	v_exp_f32_e32 v48, v40
	v_fma_f32 v49, v49, s15, -v32
	v_exp_f32_e32 v49, v49
	v_fma_f32 v50, v50, s15, -v32
	v_exp_f32_e32 v50, v50
	v_fma_f32 v51, v51, s15, -v32
	v_exp_f32_e32 v51, v51
	v_fma_f32 v52, v52, s15, -v32
	v_add_f32_e32 v128, 0, v48
	v_exp_f32_e32 v52, v52
	v_fma_f32 v53, v53, s15, -v32
	v_add_f32_e32 v128, v49, v128
	v_exp_f32_e32 v53, v53
	v_fma_f32 v54, v54, s15, -v32
	v_add_f32_e32 v128, v50, v128
	v_exp_f32_e32 v54, v54
	v_fma_f32 v55, v55, s15, -v32
	v_add_f32_e32 v128, v51, v128
	v_exp_f32_e32 v55, v55
	v_fma_f32 v56, v56, s15, -v32
	v_add_f32_e32 v128, v52, v128
	v_exp_f32_e32 v56, v56
	v_fma_f32 v57, v57, s15, -v32
	v_add_f32_e32 v128, v53, v128
	v_exp_f32_e32 v57, v57
	v_fma_f32 v58, v58, s15, -v32
	v_add_f32_e32 v128, v54, v128
	v_exp_f32_e32 v58, v58
	v_fma_f32 v59, v59, s15, -v32
	v_add_f32_e32 v128, v55, v128
	v_exp_f32_e32 v59, v59
	v_fma_f32 v60, v60, s15, -v32
	v_add_f32_e32 v128, v56, v128
	v_exp_f32_e32 v60, v60
	v_fma_f32 v61, v61, s15, -v32
	v_add_f32_e32 v128, v57, v128
	v_exp_f32_e32 v61, v61
	v_fma_f32 v62, v62, s15, -v32
	v_add_f32_e32 v128, v58, v128
	v_exp_f32_e32 v62, v62
	v_fma_f32 v63, v63, s15, -v32
	v_sub_f32_e32 v40, v176, v32
	v_add_f32_e32 v128, v59, v128
	v_exp_f32_e32 v63, v63
	v_fma_f32 v176, v178, s15, -v32
	v_add_f32_e32 v128, v60, v128
	v_exp_f32_e32 v176, v176
	v_fma_f32 v33, v33, s15, -v32
	v_add_f32_e32 v128, v61, v128
	v_exp_f32_e32 v33, v33
	v_fma_f32 v34, v34, s15, -v32
	v_add_f32_e32 v128, v62, v128
	v_exp_f32_e32 v177, v34
	v_fma_f32 v34, v35, s15, -v32
	v_add_f32_e32 v128, v63, v128
	v_exp_f32_e32 v178, v34
	v_fma_f32 v34, v36, s15, -v32
	v_add_f32_e32 v128, v176, v128
	v_exp_f32_e32 v180, v34
	v_fma_f32 v35, v37, s15, -v32
	v_add_f32_e32 v34, v33, v128
	v_exp_f32_e32 v128, v35
	v_fma_f32 v35, v38, s15, -v32
	v_add_f32_e32 v34, v177, v34
	v_exp_f32_e32 v38, v35
	v_fma_f32 v35, v39, s15, -v32
	v_add_f32_e32 v34, v178, v34
	v_exp_f32_e32 v39, v35
	v_add_f32_e32 v34, v180, v34
	v_exp_f32_e32 v40, v40
	v_add_f32_e32 v34, v128, v34
	v_add_f32_e32 v34, v38, v34
	v_add_f32_e32 v181, v39, v34
	v_fma_f32 v34, v179, s15, -v32
	v_exp_f32_e32 v179, v34
	v_pk_mul_f32 v[14:15], v[14:15], v[40:41] op_sel_hi:[1,0]
	v_pk_mul_f32 v[12:13], v[12:13], v[40:41] op_sel_hi:[1,0]
	v_pk_mul_f32 v[10:11], v[10:11], v[40:41] op_sel_hi:[1,0]
	v_pk_mul_f32 v[8:9], v[8:9], v[40:41] op_sel_hi:[1,0]
	v_pk_mul_f32 v[6:7], v[6:7], v[40:41] op_sel_hi:[1,0]
	v_pk_mul_f32 v[4:5], v[4:5], v[40:41] op_sel_hi:[1,0]
	v_pk_mul_f32 v[2:3], v[2:3], v[40:41] op_sel_hi:[1,0]
	v_pk_mul_f32 v[0:1], v[0:1], v[40:41] op_sel_hi:[1,0]
	v_pk_mul_f32 v[30:31], v[30:31], v[40:41] op_sel_hi:[1,0]
	v_cvt_pk_bf16_f32 v34, v48, v49
	v_cvt_pk_bf16_f32 v35, v50, v51
	v_cvt_pk_bf16_f32 v36, v52, v53
	v_cvt_pk_bf16_f32 v37, v54, v55
	v_pk_mul_f32 v[28:29], v[28:29], v[40:41] op_sel_hi:[1,0]
	v_pk_mul_f32 v[26:27], v[26:27], v[40:41] op_sel_hi:[1,0]
	v_pk_mul_f32 v[24:25], v[24:25], v[40:41] op_sel_hi:[1,0]
	v_pk_mul_f32 v[22:23], v[22:23], v[40:41] op_sel_hi:[1,0]
	v_pk_mul_f32 v[20:21], v[20:21], v[40:41] op_sel_hi:[1,0]
	v_pk_mul_f32 v[18:19], v[18:19], v[40:41] op_sel_hi:[1,0]
	v_pk_mul_f32 v[16:17], v[16:17], v[40:41] op_sel_hi:[1,0]
	v_mfma_f32_32x32x16_bf16 v[0:15], v[124:127], v[34:37], v[0:15]
	v_fma_f32 v42, v42, s15, -v32
	v_exp_f32_e32 v42, v42
	v_fma_f32 v43, v43, s15, -v32
	v_exp_f32_e32 v43, v43
	v_fma_f32 v44, v44, s15, -v32
	v_add_f32_e32 v48, v179, v181
	v_exp_f32_e32 v44, v44
	v_mfma_f32_32x32x16_bf16 v[16:31], v[120:123], v[34:37], v[16:31]
	v_fma_f32 v34, v41, s15, -v32
	v_exp_f32_e32 v41, v34
	v_cvt_pk_bf16_f32 v34, v56, v57
	v_cvt_pk_bf16_f32 v35, v58, v59
	v_cvt_pk_bf16_f32 v36, v60, v61
	v_cvt_pk_bf16_f32 v37, v62, v63
	v_add_f32_e32 v48, v41, v48
	s_cmp_ge_u32 s0, s11
	v_mfma_f32_32x32x16_bf16 v[0:15], v[116:119], v[34:37], v[0:15]
	v_mfma_f32_32x32x16_bf16 v[16:31], v[112:115], v[34:37], v[16:31]
	v_add_f32_e32 v34, v42, v48
	v_add_f32_e32 v34, v43, v34
	v_add_f32_e32 v48, v44, v34
	v_cvt_pk_bf16_f32 v34, v176, v33
	v_cvt_pk_bf16_f32 v35, v177, v178
	v_cvt_pk_bf16_f32 v36, v180, v128
	v_cvt_pk_bf16_f32 v37, v38, v39
	v_fma_f32 v33, v45, s15, -v32
	v_fma_f32 v38, v46, s15, -v32
	v_mfma_f32_32x32x16_bf16 v[0:15], v[108:111], v[34:37], v[0:15]
	v_exp_f32_e32 v33, v33
	v_exp_f32_e32 v39, v38
	v_fma_f32 v38, v47, s15, -v32
	v_exp_f32_e32 v45, v38
	v_add_f32_e32 v38, v33, v48
	v_mfma_f32_32x32x16_bf16 v[16:31], v[104:107], v[34:37], v[16:31]
	v_add_f32_e32 v34, v39, v38
	v_cvt_pk_bf16_f32 v36, v179, v41
	v_cvt_pk_bf16_f32 v37, v42, v43
	v_cvt_pk_bf16_f32 v38, v44, v33
	v_cvt_pk_bf16_f32 v39, v39, v45
	v_add_f32_e32 v34, v45, v34
	ds_bpermute_b32 v35, v174, v34
	v_mfma_f32_32x32x16_bf16 v[0:15], v[100:103], v[36:39], v[0:15]
	s_waitcnt lgkmcnt(0)
	v_add_f32_e32 v34, v34, v35
	v_fmac_f32_e32 v34, v175, v40
	v_mfma_f32_32x32x16_bf16 v[16:31], v[96:99], v[36:39], v[16:31]
	s_cbranch_scc1 .LBB0_1659
	v_mov_b32_e32 v175, v34
	v_mov_b32_e32 v176, v32
	s_branch .LBB0_1668
